# branch-merge GEMM phases: one-sleep start stagger for odd in-XCD blocks (as the in-proj phase has), on top of v56
# speedup vs baseline: 1.0236x; 1.0005x over previous
.LBB0_198:
	s_andn2_b64 vcc, exec, s[4:5]
	s_cbranch_vccnz .LBB0_330
	v_readlane_b32 s98, v255, 18
	s_bitcmp0_b32 s98, 3
	s_cbranch_scc1 .Lstag_skip_br
	s_sleep 0x7f
.Lstag_skip_br:
	v_bfe_i32 v2, v0, 27, 1
	v_lshlrev_b32_e32 v4, 4, v0
	v_lshrrev_b32_e32 v2, 22, v2
	v_add_u32_e32 v2, v4, v2
	v_and_b32_e32 v2, 0xfffffc00, v2
	v_sub_u32_e32 v2, v4, v2
	v_lshrrev_b32_e32 v3, 4, v2
	v_bitop3_b32 v3, v3, v2, 32 bitop3:0x6c
	v_ashrrev_i32_e32 v2, 31, v2
	v_lshrrev_b32_e32 v2, 26, v2
	v_ashrrev_i32_e32 v1, 31, v0
	v_add_u32_e32 v2, v3, v2
	v_lshrrev_b32_e32 v1, 26, v1
	v_ashrrev_i32_e32 v2, 6, v2
	v_add_u32_e32 v1, v0, v1
	v_mul_i32_i24_e32 v7, 64, v2
	v_ashrrev_i32_e32 v1, 6, v1
	v_sub_u32_e32 v3, v3, v7
	v_lshlrev_b32_e32 v5, 3, v1
	v_lshlrev_b32_e32 v6, 5, v1
	v_ashrrev_i16_sdwa v3, v230, sext(v3) dst_sel:DWORD dst_unused:UNUSED_PAD src0_sel:DWORD src1_sel:BYTE_0
	v_and_b32_e32 v5, -16, v5
	v_and_b32_e32 v6, 32, v6
	v_bfe_i32 v3, v3, 0, 16
	v_add_u32_e32 v5, v2, v5
	v_and_b32_e32 v9, 3, v2
	s_mov_b32 s4, 0x3fffe0
	v_add_lshl_u32 v6, v6, v3, 1
	v_lshlrev_b32_e32 v7, 1, v5
	v_lshrrev_b32_e32 v8, 2, v5
	v_and_or_b32 v9, v5, s4, v9
	v_lshl_add_u32 v208, v5, 10, v6
	v_add_u32_e32 v5, 0x2000, v4
	v_ashrrev_i32_e32 v4, 31, v5
	v_lshrrev_b32_e32 v4, 22, v4
	v_and_b32_e32 v7, 24, v7
	v_and_b32_e32 v8, 4, v8
	v_add_u32_e32 v4, v5, v4
	v_or3_b32 v7, v9, v8, v7
	v_ashrrev_i32_e32 v4, 10, v4
	v_lshl_add_u32 v16, v7, 10, v6
	v_mul_i32_i24_e32 v6, 0x400, v4
	v_sub_u32_e32 v5, v5, v6
	v_lshrrev_b32_e32 v6, 4, v5
	v_bitop3_b32 v6, v6, v5, 32 bitop3:0x6c
	v_lshlrev_b32_e32 v5, 3, v4
	v_and_b32_e32 v7, -16, v5
	v_ashrrev_i32_e32 v5, 31, v6
	v_lshrrev_b32_e32 v5, 26, v5
	v_add_u32_e32 v8, v6, v5
	v_ashrrev_i32_e32 v5, 6, v8
	s_add_u32 s37, s44, 0x2200000
	v_add_u32_e32 v7, v5, v7
	v_and_b32_e32 v11, 3, v5
	s_addc_u32 s48, s45, 0
	v_and_or_b32 v11, v7, s4, v11
	s_ashr_i32 s4, s79, 6
	s_ashr_i32 s2, s79, 8
	s_lshl_b32 s49, s4, 10
	s_add_u32 s50, s44, 0x190c0000
	s_addc_u32 s51, s45, 0
	s_ashr_i32 s9, s8, 31
	s_ashr_i32 s15, s14, 31
	v_and_b32_e32 v8, 0xc0, v8
	s_lshl_b64 s[18:19], s[8:9], 18
	s_lshl_b64 s[16:17], s[14:15], 18
	v_sub_u32_e32 v6, v6, v8
	s_add_u32 s16, s37, s16
	v_lshlrev_b32_e32 v9, 5, v4
	v_ashrrev_i16_sdwa v6, v230, sext(v6) dst_sel:DWORD dst_unused:UNUSED_PAD src0_sel:DWORD src1_sel:BYTE_0
	v_lshlrev_b32_e32 v8, 1, v7
	v_lshrrev_b32_e32 v10, 2, v7
	s_addc_u32 s17, s48, s17
	s_add_i32 s52, s49, 0
	v_and_b32_e32 v9, 32, v9
	v_bfe_i32 v6, v6, 0, 16
	v_and_b32_e32 v8, 24, v8
	v_and_b32_e32 v10, 4, v10
	s_add_i32 m0, s52, 0x10000
	v_or3_b32 v8, v11, v10, v8
	v_add_lshl_u32 v9, v9, v6, 1
	global_load_lds_dwordx4 v16, s[16:17]
	s_add_i32 m0, s52, 0x12000
	v_lshl_add_u32 v212, v8, 10, v9
	s_add_u32 s18, s50, s18
	global_load_lds_dwordx4 v212, s[16:17]
	s_addc_u32 s19, s51, s19
	s_mov_b32 m0, s52
	s_add_i32 s58, s52, 0x2000
	v_lshl_add_u32 v210, v7, 10, v9
	global_load_lds_dwordx4 v208, s[18:19]
	s_mov_b32 m0, s58
	s_add_u32 s22, s16, 0x20000
	global_load_lds_dwordx4 v210, s[18:19]
	s_addc_u32 s23, s17, 0
	s_add_i32 m0, s52, 0x14000
	v_writelane_b32 v255, s34, 30
	global_load_lds_dwordx4 v16, s[22:23]
	s_add_i32 m0, s52, 0x16000
	v_writelane_b32 v255, s35, 31
	global_load_lds_dwordx4 v212, s[22:23]
	s_add_u32 s22, s18, 0x20000
	s_addc_u32 s23, s19, 0
	s_add_i32 s59, s52, 0x4000
	s_mov_b32 m0, s59
	s_add_i32 s60, s52, 0x6000
	global_load_lds_dwordx4 v208, s[22:23]
	s_mov_b32 m0, s60
	s_cmp_lg_u32 s2, 1
	global_load_lds_dwordx4 v210, s[22:23]
	s_cbranch_scc1 .LBB0_201
	s_barrier
